# FFN up epilogue: conv weight/bias lines touched at epilogue start (cache prefetch) on top of GEMM half re-alignment
# baseline (speedup 1.0000x reference)
; #define LAS __attribute__((address_space(3)))
;     __device__ __forceinline__ void operator()(const f32x4 (&acc_c)[2][2][4][2], const Unit& u, int wr, int wc, int fr, int fq) const {
;     ...
;         float rsv[2][4];
; #pragma unroll
;         for (int ai = 0; ai < 2; ++ai)
; #pragma unroll
;             for (int m = 0; m < 4; ++m) rsv[ai][m] = rowsq[row0 + ai * HALF + m * 16];
; #pragma unroll
;         for (int ai = 0; ai < 2; ++ai)
; #pragma unroll
;             for (int m = 0; m < 4; ++m) { const float rs = rsqrtf(rsv[ai][m] * (1.0f / 1024.0f) + EPS);
; #pragma unroll
;                 for (int bj = 0; bj < 2; ++bj)
; #pragma unroll
;                     for (int n = 0; n < 2; ++n) acc[ai][bj][m][n] *= rs; }
;         if (fr >= 14) {
; #pragma unroll
;             for (int ai = 0; ai < 2; ++ai)
; #pragma unroll
;                 for (int bj = 0; bj < 2; ++bj)
; #pragma unroll
;                     for (int n = 0; n < 2; ++n) *(LAS f32x4*)(xch + ((ai * 2 + wr) * 4 + wc) * 128 + (fr - 14) * 64 + bj * 32 + 8 * fq + 4 * n) = acc[ai][bj][3][n];
;         }
;     ...
;             for (int t = 0; t < 3; ++t) { wg[t] = *(const f32x4*)(cw + t * FF2 + ch0 + 4 * n); wv[t] = *(const f32x4*)(cw + t * FF2 + FF + ch0 + 4 * n); }
;             bg = *(const f32x4*)(cb + ch0 + 4 * n); bv = *(const f32x4*)(cb + FF + ch0 + 4 * n);
.Lalign_up_a:
	v_lshl_or_b32 v250, s72, 7, v170
	v_ashrrev_i32_e32 v251, 31, v250
	v_lshlrev_b64 v[250:251], 2, v[250:251]
	v_lshl_add_u64 v[242:243], s[16:17], 0, v[250:251]
	global_load_dword v241, v[242:243], off
	v_lshl_add_u64 v[242:243], s[26:27], 0, v[250:251]
	global_load_dword v241, v[242:243], off
	v_lshl_add_u64 v[242:243], s[28:29], 0, v[250:251]
	global_load_dword v241, v[242:243], off
	v_lshl_add_u64 v[242:243], s[30:31], 0, v[250:251]
	global_load_dword v241, v[242:243], off
	v_lshl_add_u64 v[242:243], s[34:35], 0, v[250:251]
	global_load_dword v241, v[242:243], off
	v_lshl_add_u64 v[242:243], s[36:37], 0, v[250:251]
	global_load_dword v241, v[242:243], off
	v_lshl_add_u64 v[242:243], s[18:19], 0, v[250:251]
	global_load_dword v241, v[242:243], off
	v_lshl_add_u64 v[242:243], s[38:39], 0, v[250:251]
	global_load_dword v241, v[242:243], off
	v_lshl_add_u32 v192, s4, 8, v161
	v_or_b32_e32 v198, 16, v192
	v_ashrrev_i32_e32 v193, 31, v192
	v_ashrrev_i32_e32 v199, 31, v198
	v_or_b32_e32 v196, 32, v192
	v_lshl_add_u64 v[114:115], v[192:193], 2, s[14:15]
	v_lshl_add_u64 v[116:117], v[198:199], 2, s[14:15]
	v_ashrrev_i32_e32 v197, 31, v196
	v_or_b32_e32 v194, 48, v192
	global_load_dword v0, v[114:115], off
	global_load_dword v190, v[116:117], off
	v_lshl_add_u64 v[116:117], v[196:197], 2, s[14:15]
	v_ashrrev_i32_e32 v195, 31, v194
	global_load_dword v147, v[116:117], off
	v_lshl_add_u64 v[116:117], v[194:195], 2, s[14:15]
	global_load_dword v116, v[116:117], off
	s_nop 0
	global_load_dword v195, v[114:115], off offset:512
	global_load_dword v193, v[114:115], off offset:576
	global_load_dword v191, v[114:115], off offset:640
	s_nop 0
	global_load_dword v115, v[114:115], off offset:704
	s_waitcnt vmcnt(0)
	v_fmamk_f32 v114, v116, 0x3a800000, v216
	v_cmp_gt_f32_e32 vcc, s2, v114
	v_mul_f32_e32 v116, 0x4b800000, v114
	s_nop 0
	v_cndmask_b32_e32 v114, v114, v116, vcc
	v_rsq_f32_e32 v114, v114
	s_nop 0
	v_mul_f32_e32 v116, 0x45800000, v114
	v_cndmask_b32_e32 v114, v114, v116, vcc
	v_pk_mul_f32 v[138:139], v[106:107], v[114:115] op_sel_hi:[1,0]
	v_fmamk_f32 v106, v115, 0x3a800000, v216
	v_cmp_gt_f32_e32 vcc, s2, v106
	v_mul_f32_e32 v107, 0x4b800000, v106
	v_pk_mul_f32 v[144:145], v[112:113], v[114:115] op_sel_hi:[1,0]
	v_cndmask_b32_e32 v106, v106, v107, vcc
	v_rsq_f32_e32 v106, v106
	v_pk_mul_f32 v[142:143], v[110:111], v[114:115] op_sel_hi:[1,0]
	v_pk_mul_f32 v[56:57], v[56:57], v[114:115] op_sel_hi:[1,0]
	v_pk_mul_f32 v[54:55], v[54:55], v[114:115] op_sel_hi:[1,0]
	v_mul_f32_e32 v107, 0x45800000, v106
	v_cndmask_b32_e32 v106, v106, v107, vcc
	v_pk_mul_f32 v[140:141], v[108:109], v[114:115] op_sel_hi:[1,0]
	v_pk_mul_f32 v[52:53], v[52:53], v[114:115] op_sel_hi:[1,0]
	v_pk_mul_f32 v[50:51], v[50:51], v[114:115] op_sel_hi:[1,0]
	v_pk_mul_f32 v[88:89], v[88:89], v[106:107] op_sel_hi:[1,0]
	v_pk_mul_f32 v[86:87], v[86:87], v[106:107] op_sel_hi:[1,0]
	v_pk_mul_f32 v[28:29], v[28:29], v[106:107] op_sel_hi:[1,0]
	v_pk_mul_f32 v[26:27], v[26:27], v[106:107] op_sel_hi:[1,0]
	v_pk_mul_f32 v[84:85], v[84:85], v[106:107] op_sel_hi:[1,0]
	v_pk_mul_f32 v[82:83], v[82:83], v[106:107] op_sel_hi:[1,0]
	v_pk_mul_f32 v[32:33], v[32:33], v[106:107] op_sel_hi:[1,0]
	v_pk_mul_f32 v[30:31], v[30:31], v[106:107] op_sel_hi:[1,0]
	s_and_saveexec_b64 s[48:49], s[6:7]
	s_cbranch_execz .LBB0_1438
	ds_write_b128 v228, v[142:145]
	ds_write_b128 v229, v[54:57]
	ds_write_b128 v230, v[138:141]
	ds_write_b128 v231, v[50:53]
	ds_write_b128 v227, v[86:89] offset:512
	ds_write_b128 v227, v[26:29] offset:528
	ds_write_b128 v227, v[82:85] offset:640
	ds_write_b128 v227, v[30:33] offset:656
